# P6' panel groups of an XCD start ~1us apart (on top of XCD-local seams, 3us XCD stagger, P4/P6' epilogue rewrites)
# speedup vs baseline: 1.0140x; 1.0013x over previous
.LBB0_566:
	s_or_b64 exec, exec, s[4:5]
	s_add_u32 s14, s66, 0x64000
	s_addc_u32 s15, s67, 0
	s_add_u32 s16, s66, 0x20000
	s_addc_u32 s17, s67, 0
	v_readlane_b32 s98, v255, 0
	s_nop 3
	s_cmp_eq_u32 s98, 0
	s_cbranch_scc1 .Lps_done
	s_lshr_b32 s98, s2, 6
	s_and_b32 s98, s98, 3
	s_cmp_eq_u32 s98, 0
	s_cbranch_scc1 .Lps_done
.Lps_loop:
	s_sleep 32
	s_add_i32 s98, s98, -1
	s_cmp_lg_u32 s98, 0
	s_cbranch_scc1 .Lps_loop
.Lps_done:
	s_cmpk_lg_i32 s3, 0x100
	s_mov_b64 s[4:5], -1
	s_waitcnt lgkmcnt(0)
	s_barrier
	s_cbranch_scc0 .LBB0_667
	s_and_b64 vcc, exec, s[10:11]
	v_mbcnt_lo_u32_b32 v4, -1, 0
	v_mbcnt_hi_u32_b32 v4, -1, v4
	s_cbranch_vccnz .LBB0_573
	s_ashr_i32 s4, s2, 31
	s_lshr_b32 s4, s4, 29
	s_add_i32 s8, s2, s4
	s_and_b32 s4, s8, -8
	s_sub_i32 s6, s2, s4
	s_cmp_gt_i32 s6, -1
	s_cbranch_scc0 .LBB0_570
	s_lshl_b32 s7, s6, 6
	s_ashr_i32 s4, s8, 3
	s_cbranch_execz .LBB0_571
	s_branch .LBB0_572
